# prologue: rotary cos/sin table's 4 serial position loads batched; adaLN GEMV second pass's 16 row loads issued with the first pass's (shadow registers)
# speedup vs baseline: 1.0040x; 1.0040x over previous
; #define LAS __attribute__((address_space(3)))
; #define LAS __attribute__((address_space(3)))
; __device__ __forceinline__ void prologue(const Args& a, LAS unsigned char* lds) {
;     ...
;             for (int kh = 0; kh < KPI; kh += 16) {
;                 float wv[16];
; #pragma unroll
;                 for (int k = 0; k < 16; ++k) wv[k] = __builtin_nontemporal_load(w + (size_t)(kh + k) * NMODW);
; #pragma unroll
;                 for (int k = 0; k < 16; ++k) {
;                     const LAS float* sp = sc + kc * KPI + kh + k;
; #pragma unroll
;                     for (int b = 0; b < 8; ++b) acc[b] += sp[b * DM] * wv[k];
.LBB0_11:
	s_cmp_eq_u32 s30, 0
	s_cselect_b32 s101, 1, 0
	s_mov_b32 s98, 0x60000
	s_mov_b32 s99, 0
	s_mul_i32 s4, s30, 0x1800
	s_lshl_b32 s0, s30, 2
	v_lshl_add_u64 v[14:15], s[4:5], 2, v[4:5]
	s_add_i32 s8, s7, s0
	v_add_co_u32_e64 v46, s[0:1], s3, v14
	s_cmp_lg_u32 s101, 0
	s_cbranch_scc0 .Lgv_second_a
	global_load_dword v144, v[14:15], off nt
	v_lshl_add_u64 v[232:233], v[14:15], 0, s[98:99]
	global_load_dword v200, v[232:233], off nt
.Lgv_second_a:
	s_nop 0
	v_addc_co_u32_e64 v47, s[0:1], 0, v15, s[0:1]
	v_add_co_u32_e64 v48, s[0:1], s14, v14
	v_cndmask_b32_e64 v16, 0, 1, s[12:13]
	s_nop 0
	v_addc_co_u32_e64 v49, s[0:1], 0, v15, s[0:1]
	v_add_co_u32_e64 v50, s[0:1], s15, v14
	v_mov_b32_e32 v75, s8
	s_nop 0
	v_addc_co_u32_e64 v51, s[0:1], 0, v15, s[0:1]
	v_add_co_u32_e64 v52, s[0:1], s16, v14
	v_cmp_ne_u32_e32 vcc, 1, v16
	s_nop 0
	v_addc_co_u32_e64 v53, s[0:1], 0, v15, s[0:1]
	v_add_co_u32_e64 v54, s[0:1], s18, v14
	s_mov_b32 s30, 16
	s_nop 0
	v_addc_co_u32_e64 v55, s[0:1], 0, v15, s[0:1]
	v_add_co_u32_e64 v56, s[0:1], s19, v14
	s_mov_b64 s[12:13], 0
	s_nop 0
	v_addc_co_u32_e64 v57, s[0:1], 0, v15, s[0:1]
	v_add_co_u32_e64 v58, s[0:1], s17, v14
	s_and_b64 vcc, exec, vcc
	s_nop 0
	v_addc_co_u32_e64 v59, s[0:1], 0, v15, s[0:1]
	v_add_co_u32_e64 v60, s[0:1], s20, v14
	s_nop 1
	v_addc_co_u32_e64 v61, s[0:1], 0, v15, s[0:1]
	v_add_co_u32_e64 v62, s[0:1], s21, v14
	s_nop 1
	v_addc_co_u32_e64 v63, s[0:1], 0, v15, s[0:1]
	v_add_co_u32_e64 v64, s[0:1], s22, v14
	s_nop 1
	v_addc_co_u32_e64 v65, s[0:1], 0, v15, s[0:1]
	v_add_co_u32_e64 v66, s[0:1], s23, v14
	s_nop 1
	v_addc_co_u32_e64 v67, s[0:1], 0, v15, s[0:1]
	v_add_co_u32_e64 v68, s[0:1], s24, v14
	s_nop 1
	v_addc_co_u32_e64 v69, s[0:1], 0, v15, s[0:1]
	v_add_co_u32_e64 v70, s[0:1], s25, v14
	s_nop 1
	v_addc_co_u32_e64 v71, s[0:1], 0, v15, s[0:1]
	v_add_co_u32_e64 v72, s[0:1], s26, v14
	s_nop 1
	v_addc_co_u32_e64 v73, s[0:1], 0, v15, s[0:1]
	v_add_co_u32_e64 v76, s[0:1], s27, v14
	s_nop 1
	v_addc_co_u32_e64 v77, s[0:1], 0, v15, s[0:1]
	ds_read_b128 v[14:17], v75 offset:20480
	ds_read_b128 v[18:21], v75 offset:16384
	ds_read_b128 v[22:25], v75 offset:12288
	ds_read_b128 v[26:29], v75 offset:8192
	ds_read_b128 v[30:33], v75 offset:4096
	ds_read_b128 v[34:37], v75
	ds_read_b128 v[38:41], v75 offset:28672
	ds_read_b128 v[42:45], v75 offset:24576
	s_cmp_lg_u32 s101, 0
	s_cbranch_scc0 .Lgv_second_b
	global_load_dword v146, v[54:55], off nt
	global_load_dword v147, v[56:57], off nt
	global_load_dword v148, v[46:47], off nt
	global_load_dword v150, v[48:49], off nt
	global_load_dword v152, v[50:51], off nt
	global_load_dword v154, v[52:53], off nt
	global_load_dword v156, v[58:59], off nt
	global_load_dword v158, v[60:61], off nt
	global_load_dword v159, v[62:63], off nt
	global_load_dword v160, v[64:65], off nt
	global_load_dword v161, v[66:67], off nt
	global_load_dword v162, v[68:69], off nt
	global_load_dword v163, v[70:71], off nt
	global_load_dword v164, v[72:73], off nt
	global_load_dword v166, v[76:77], off nt
	v_lshl_add_u64 v[232:233], v[54:55], 0, s[98:99]
	global_load_dword v201, v[232:233], off nt
	v_lshl_add_u64 v[232:233], v[56:57], 0, s[98:99]
	global_load_dword v202, v[232:233], off nt
	v_lshl_add_u64 v[232:233], v[46:47], 0, s[98:99]
	global_load_dword v203, v[232:233], off nt
	v_lshl_add_u64 v[232:233], v[48:49], 0, s[98:99]
	global_load_dword v204, v[232:233], off nt
	v_lshl_add_u64 v[232:233], v[50:51], 0, s[98:99]
	global_load_dword v205, v[232:233], off nt
	v_lshl_add_u64 v[232:233], v[52:53], 0, s[98:99]
	global_load_dword v206, v[232:233], off nt
	v_lshl_add_u64 v[232:233], v[58:59], 0, s[98:99]
	global_load_dword v207, v[232:233], off nt
	v_lshl_add_u64 v[232:233], v[60:61], 0, s[98:99]
	global_load_dword v208, v[232:233], off nt
	v_lshl_add_u64 v[232:233], v[62:63], 0, s[98:99]
	global_load_dword v209, v[232:233], off nt
	v_lshl_add_u64 v[232:233], v[64:65], 0, s[98:99]
	global_load_dword v210, v[232:233], off nt
	v_lshl_add_u64 v[232:233], v[66:67], 0, s[98:99]
	global_load_dword v211, v[232:233], off nt
	v_lshl_add_u64 v[232:233], v[68:69], 0, s[98:99]
	global_load_dword v212, v[232:233], off nt
	v_lshl_add_u64 v[232:233], v[70:71], 0, s[98:99]
	global_load_dword v213, v[232:233], off nt
	v_lshl_add_u64 v[232:233], v[72:73], 0, s[98:99]
	global_load_dword v214, v[232:233], off nt
	v_lshl_add_u64 v[232:233], v[76:77], 0, s[98:99]
	global_load_dword v215, v[232:233], off nt
	s_branch .Lgv_loads_done
.Lgv_second_b:
	s_waitcnt vmcnt(0)
	v_mov_b32_e32 v144, v200
	v_mov_b32_e32 v146, v201
	v_mov_b32_e32 v147, v202
	v_mov_b32_e32 v148, v203
	v_mov_b32_e32 v150, v204
	v_mov_b32_e32 v152, v205
	v_mov_b32_e32 v154, v206
	v_mov_b32_e32 v156, v207
	v_mov_b32_e32 v158, v208
	v_mov_b32_e32 v159, v209
	v_mov_b32_e32 v160, v210
	v_mov_b32_e32 v161, v211
	v_mov_b32_e32 v162, v212
	v_mov_b32_e32 v163, v213
	v_mov_b32_e32 v164, v214
	v_mov_b32_e32 v166, v215
; #define LAS __attribute__((address_space(3)))
; #define LAS __attribute__((address_space(3)))
; __device__ __forceinline__ void prologue(const Args& a, LAS unsigned char* lds) {
;     ...
; #pragma unroll
;                 for (int k = 0; k < 16; ++k) {
;                     const LAS float* sp = sc + kc * KPI + kh + k;
; #pragma unroll
;                     for (int b = 0; b < 8; ++b) acc[b] += sp[b * DM] * wv[k];
;                     if ((k & 3) == 3) asm volatile("" ::: "memory");
;                 }
.Lgv_loads_done:
	s_waitcnt lgkmcnt(6)
	v_mov_b32_e32 v168, v18
	v_mov_b32_e32 v169, v14
	v_mov_b32_e32 v14, v19
	v_mov_b32_e32 v18, v20
	v_mov_b32_e32 v19, v16
	v_mov_b32_e32 v16, v21
	s_waitcnt lgkmcnt(4)
	v_mov_b32_e32 v20, v26
	v_mov_b32_e32 v21, v22
	v_mov_b32_e32 v22, v27
	v_mov_b32_e32 v26, v28
	v_mov_b32_e32 v27, v24
	v_mov_b32_e32 v24, v29
	s_waitcnt lgkmcnt(2)
	v_mov_b32_e32 v28, v34
	v_mov_b32_e32 v29, v30
	ds_read_b128 v[46:49], v75 offset:16
	ds_read_b128 v[50:53], v75 offset:4112
	ds_read_b128 v[54:57], v75 offset:8208
	ds_read_b128 v[58:61], v75 offset:12304
	ds_read_b128 v[62:65], v75 offset:16400
	ds_read_b128 v[66:69], v75 offset:20496
	ds_read_b128 v[70:73], v75 offset:24592
	ds_read_b128 v[76:79], v75 offset:28688
	v_mov_b32_e32 v30, v35
	s_waitcnt vmcnt(15)
	v_pk_fma_f32 v[8:9], v[144:145], v[168:169], v[8:9] op_sel_hi:[0,1,1]
	v_pk_fma_f32 v[10:11], v[144:145], v[20:21], v[10:11] op_sel_hi:[0,1,1]
	v_pk_fma_f32 v[12:13], v[144:145], v[28:29], v[12:13] op_sel_hi:[0,1,1]
	ds_read_b128 v[80:83], v75 offset:4128
	ds_read_b128 v[84:87], v75 offset:32
	ds_read_b128 v[88:91], v75 offset:12320
	ds_read_b128 v[92:95], v75 offset:8224
	ds_read_b128 v[96:99], v75 offset:16416
	ds_read_b128 v[100:103], v75 offset:20512
	ds_read_b128 v[104:107], v75 offset:24608
	ds_read_b128 v[108:111], v75 offset:28704
	v_mov_b32_e32 v34, v36
	v_mov_b32_e32 v35, v32
	v_mov_b32_e32 v32, v37
	s_waitcnt lgkmcnt(14)
	v_mov_b32_e32 v36, v42
	v_mov_b32_e32 v37, v38
	v_mov_b32_e32 v38, v43
	v_mov_b32_e32 v42, v44
	v_mov_b32_e32 v43, v40
	v_mov_b32_e32 v40, v45
	v_mov_b32_e32 v44, v46
	v_mov_b32_e32 v45, v50
	v_mov_b32_e32 v50, v47
	v_mov_b32_e32 v46, v48
	v_mov_b32_e32 v47, v52
	v_mov_b32_e32 v52, v49
	s_waitcnt lgkmcnt(13)
	v_mov_b32_e32 v48, v54
	s_waitcnt lgkmcnt(12)
	v_mov_b32_e32 v49, v58
	v_mov_b32_e32 v58, v55
	v_mov_b32_e32 v54, v56
	v_mov_b32_e32 v55, v60
	v_mov_b32_e32 v60, v57
	s_waitcnt lgkmcnt(11)
	v_mov_b32_e32 v56, v62
	s_waitcnt lgkmcnt(10)
	v_mov_b32_e32 v57, v66
	v_pk_fma_f32 v[6:7], v[144:145], v[36:37], v[6:7] op_sel_hi:[0,1,1]
	v_mov_b32_e32 v66, v63
	v_mov_b32_e32 v62, v64
	v_mov_b32_e32 v63, v68
	v_mov_b32_e32 v68, v65
	s_waitcnt lgkmcnt(6)
	v_mov_b32_e32 v64, v84
	v_mov_b32_e32 v65, v80
	v_mov_b32_e32 v80, v85
	v_mov_b32_e32 v84, v86
	v_mov_b32_e32 v85, v82
	v_mov_b32_e32 v82, v87
	s_waitcnt lgkmcnt(4)
	v_mov_b32_e32 v86, v92
	v_mov_b32_e32 v87, v88
	v_mov_b32_e32 v88, v93
	v_mov_b32_e32 v92, v94
	v_mov_b32_e32 v93, v90
	v_mov_b32_e32 v90, v95
	s_waitcnt lgkmcnt(3)
	v_mov_b32_e32 v94, v96
	s_waitcnt lgkmcnt(2)
	v_mov_b32_e32 v95, v100
	ds_read_b128 v[112:115], v75 offset:48
	ds_read_b128 v[116:119], v75 offset:4144
	ds_read_b128 v[120:123], v75 offset:8240
	ds_read_b128 v[124:127], v75 offset:12336
	ds_read_b128 v[128:131], v75 offset:16432
	ds_read_b128 v[132:135], v75 offset:20528
	ds_read_b128 v[136:139], v75 offset:24624
	ds_read_b128 v[140:143], v75 offset:28720
	s_waitcnt vmcnt(13)
	v_pk_mul_f32 v[78:79], v[146:147], v[78:79]
	s_waitcnt vmcnt(12)
	v_pk_fma_f32 v[8:9], v[148:149], v[14:15], v[8:9] op_sel_hi:[0,1,1]
	v_pk_fma_f32 v[10:11], v[148:149], v[22:23], v[10:11] op_sel_hi:[0,1,1]
	v_pk_fma_f32 v[12:13], v[148:149], v[30:31], v[12:13] op_sel_hi:[0,1,1]
	s_waitcnt vmcnt(11)
	v_pk_fma_f32 v[8:9], v[150:151], v[18:19], v[8:9] op_sel_hi:[0,1,1]
	v_pk_fma_f32 v[10:11], v[150:151], v[26:27], v[10:11] op_sel_hi:[0,1,1]
	v_pk_fma_f32 v[12:13], v[150:151], v[34:35], v[12:13] op_sel_hi:[0,1,1]
	s_waitcnt vmcnt(8)
	v_mov_b32_e32 v155, v156
	v_pk_fma_f32 v[8:9], v[152:153], v[16:17], v[8:9] op_sel_hi:[0,1,1]
	v_pk_fma_f32 v[10:11], v[152:153], v[24:25], v[10:11] op_sel_hi:[0,1,1]
	v_pk_fma_f32 v[12:13], v[152:153], v[32:33], v[12:13] op_sel_hi:[0,1,1]
	v_pk_fma_f32 v[6:7], v[148:149], v[38:39], v[6:7] op_sel_hi:[0,1,1]
	v_pk_fma_f32 v[12:13], v[154:155], v[44:45], v[12:13] op_sel_hi:[0,1,1]
	v_pk_fma_f32 v[10:11], v[154:155], v[48:49], v[10:11] op_sel_hi:[0,1,1]
	v_pk_fma_f32 v[8:9], v[154:155], v[56:57], v[8:9] op_sel_hi:[0,1,1]
	v_pk_fma_f32 v[6:7], v[150:151], v[42:43], v[6:7] op_sel_hi:[0,1,1]
	v_pk_mul_f32 v[18:19], v[154:155], v[76:77]
	v_pk_fma_f32 v[12:13], v[156:157], v[50:51], v[12:13] op_sel_hi:[0,1,1]
	v_pk_fma_f32 v[10:11], v[156:157], v[58:59], v[10:11] op_sel_hi:[0,1,1]
	v_pk_fma_f32 v[8:9], v[156:157], v[66:67], v[8:9] op_sel_hi:[0,1,1]
	v_mov_b32_e32 v14, v147
	s_waitcnt vmcnt(7) lgkmcnt(9)
	v_mul_f32_e32 v28, v158, v104
	s_waitcnt vmcnt(6)
	v_mul_f32_e32 v30, v159, v105
	s_waitcnt lgkmcnt(8)
	v_pk_mul_f32 v[104:105], v[158:159], v[108:109]
	v_mul_f32_e32 v108, v156, v71
	v_mul_f32_e32 v70, v154, v70
	v_pk_fma_f32 v[6:7], v[152:153], v[40:41], v[6:7] op_sel_hi:[0,1,1]
	v_mov_b32_e32 v71, v18
	v_pk_fma_f32 v[12:13], v[146:147], v[46:47], v[12:13] op_sel_hi:[0,1,1]
	v_pk_fma_f32 v[10:11], v[146:147], v[54:55], v[10:11] op_sel_hi:[0,1,1]
	v_pk_fma_f32 v[8:9], v[146:147], v[62:63], v[8:9] op_sel_hi:[0,1,1]
	v_mov_b32_e32 v109, v19
	v_pk_add_f32 v[6:7], v[6:7], v[70:71]
	v_pk_fma_f32 v[12:13], v[14:15], v[52:53], v[12:13] op_sel_hi:[0,1,1]
	v_pk_fma_f32 v[10:11], v[14:15], v[60:61], v[10:11] op_sel_hi:[0,1,1]
	v_pk_fma_f32 v[8:9], v[14:15], v[68:69], v[8:9] op_sel_hi:[0,1,1]
	v_mov_b32_e32 v100, v97
	v_mov_b32_e32 v20, v159
	s_waitcnt vmcnt(5)
	v_mul_f32_e32 v36, v160, v106
	s_waitcnt vmcnt(4)
; #define LAS __attribute__((address_space(3)))
; #define LAS __attribute__((address_space(3)))
; __device__ __forceinline__ void prologue(const Args& a, LAS unsigned char* lds) {
;     ...
;                 for (int k = 0; k < 16; ++k) {
;                     const LAS float* sp = sc + kc * KPI + kh + k;
; #pragma unroll
;                     for (int b = 0; b < 8; ++b) acc[b] += sp[b * DM] * wv[k];
;                     if ((k & 3) == 3) asm volatile("" ::: "memory");
;                 }
;             }
; #pragma unroll
;             for (int b = 0; b < 8; ++b) modp[((size_t)(l * KCH + kc) * 8 + b) * NMODW + n] = acc[b];
	v_mul_f32_e32 v38, v161, v107
	v_pk_mul_f32 v[106:107], v[160:161], v[110:111]
	v_mul_f32_e32 v72, v146, v72
	v_mul_f32_e32 v110, v147, v73
	v_mov_b32_e32 v73, v78
	v_pk_add_f32 v[6:7], v[6:7], v[108:109]
	v_pk_fma_f32 v[12:13], v[158:159], v[64:65], v[12:13] op_sel_hi:[0,1,1]
	v_pk_fma_f32 v[10:11], v[158:159], v[86:87], v[10:11] op_sel_hi:[0,1,1]
	v_pk_fma_f32 v[8:9], v[158:159], v[94:95], v[8:9] op_sel_hi:[0,1,1]
	v_mov_b32_e32 v96, v98
	v_mov_b32_e32 v97, v102
	v_mov_b32_e32 v111, v79
	v_pk_add_f32 v[6:7], v[6:7], v[72:73]
	v_pk_fma_f32 v[12:13], v[20:21], v[80:81], v[12:13] op_sel_hi:[0,1,1]
	v_pk_fma_f32 v[10:11], v[20:21], v[88:89], v[10:11] op_sel_hi:[0,1,1]
	v_pk_fma_f32 v[8:9], v[20:21], v[100:101], v[8:9] op_sel_hi:[0,1,1]
	v_mov_b32_e32 v102, v99
	v_mov_b32_e32 v22, v161
	v_mov_b32_e32 v29, v104
	v_pk_add_f32 v[6:7], v[6:7], v[110:111]
	v_pk_fma_f32 v[12:13], v[160:161], v[84:85], v[12:13] op_sel_hi:[0,1,1]
	v_pk_fma_f32 v[10:11], v[160:161], v[92:93], v[10:11] op_sel_hi:[0,1,1]
	v_pk_fma_f32 v[8:9], v[160:161], v[96:97], v[8:9] op_sel_hi:[0,1,1]
	s_waitcnt lgkmcnt(7)
	v_mov_b32_e32 v98, v112
	s_waitcnt lgkmcnt(6)
	v_mov_b32_e32 v99, v116
	v_mov_b32_e32 v116, v113
	v_mov_b32_e32 v112, v114
	v_mov_b32_e32 v113, v118
	v_mov_b32_e32 v118, v115
	s_waitcnt lgkmcnt(5)
	v_mov_b32_e32 v114, v120
	s_waitcnt lgkmcnt(4)
	v_mov_b32_e32 v115, v124
	v_mov_b32_e32 v124, v121
	v_mov_b32_e32 v120, v122
	v_mov_b32_e32 v121, v126
	v_mov_b32_e32 v126, v123
	s_waitcnt lgkmcnt(3)
	v_mov_b32_e32 v122, v128
	s_waitcnt lgkmcnt(2)
	v_mov_b32_e32 v123, v132
	v_mov_b32_e32 v31, v105
	v_pk_add_f32 v[6:7], v[6:7], v[28:29]
	v_pk_fma_f32 v[12:13], v[22:23], v[82:83], v[12:13] op_sel_hi:[0,1,1]
	v_pk_fma_f32 v[10:11], v[22:23], v[90:91], v[10:11] op_sel_hi:[0,1,1]
	v_pk_fma_f32 v[8:9], v[22:23], v[102:103], v[8:9] op_sel_hi:[0,1,1]
	v_mov_b32_e32 v132, v129
	s_waitcnt vmcnt(2)
	v_mov_b32_e32 v148, v163
	v_mov_b32_e32 v37, v106
	v_pk_add_f32 v[6:7], v[6:7], v[30:31]
	v_pk_fma_f32 v[12:13], v[162:163], v[98:99], v[12:13] op_sel_hi:[0,1,1]
	v_pk_fma_f32 v[10:11], v[162:163], v[114:115], v[10:11] op_sel_hi:[0,1,1]
	v_pk_fma_f32 v[8:9], v[162:163], v[122:123], v[8:9] op_sel_hi:[0,1,1]
	v_mov_b32_e32 v128, v130
	v_mov_b32_e32 v129, v134
	s_waitcnt lgkmcnt(0)
	v_pk_mul_f32 v[140:141], v[162:163], v[140:141]
	v_mov_b32_e32 v39, v107
	v_pk_add_f32 v[6:7], v[6:7], v[36:37]
	v_pk_fma_f32 v[12:13], v[148:149], v[116:117], v[12:13] op_sel_hi:[0,1,1]
	v_pk_fma_f32 v[10:11], v[148:149], v[124:125], v[10:11] op_sel_hi:[0,1,1]
	v_pk_fma_f32 v[8:9], v[148:149], v[132:133], v[8:9] op_sel_hi:[0,1,1]
	v_mov_b32_e32 v134, v131
	v_mul_f32_e32 v130, v162, v136
	v_mov_b32_e32 v131, v140
	v_pk_add_f32 v[6:7], v[6:7], v[38:39]
	s_waitcnt vmcnt(1)
	v_pk_fma_f32 v[12:13], v[164:165], v[112:113], v[12:13] op_sel_hi:[0,1,1]
	v_pk_fma_f32 v[10:11], v[164:165], v[120:121], v[10:11] op_sel_hi:[0,1,1]
	v_pk_fma_f32 v[8:9], v[164:165], v[128:129], v[8:9] op_sel_hi:[0,1,1]
	s_waitcnt vmcnt(0)
	v_mov_b32_e32 v165, v166
	v_mul_f32_e32 v136, v163, v137
	v_mov_b32_e32 v137, v141
	v_pk_add_f32 v[6:7], v[6:7], v[130:131]
	v_pk_mul_f32 v[14:15], v[164:165], v[142:143]
	v_mul_f32_e32 v138, v164, v138
	v_mul_f32_e32 v144, v166, v139
	v_pk_add_f32 v[6:7], v[6:7], v[136:137]
	v_mov_b32_e32 v139, v14
	v_mov_b32_e32 v145, v15
	v_pk_add_f32 v[6:7], v[6:7], v[138:139]
	v_pk_fma_f32 v[12:13], v[166:167], v[118:119], v[12:13] op_sel_hi:[0,1,1]
	v_pk_fma_f32 v[10:11], v[166:167], v[126:127], v[10:11] op_sel_hi:[0,1,1]
	v_pk_fma_f32 v[8:9], v[166:167], v[134:135], v[8:9] op_sel_hi:[0,1,1]
	v_pk_add_f32 v[6:7], v[6:7], v[144:145]
	s_cbranch_vccz .LBB0_11
	s_lshl_b32 s0, s6, 5
	s_add_i32 s0, s0, s29
	v_lshl_add_u64 v[2:3], v[2:3], 2, s[34:35]
	v_mad_i64_i32 v[2:3], s[0:1], s0, v1, v[2:3]
	v_add_co_u32_e32 v4, vcc, 0x6000, v2
	global_store_dword v[2:3], v12, off
	s_nop 0
	v_addc_co_u32_e32 v5, vcc, 0, v3, vcc
	global_store_dword v[4:5], v13, off
	v_add_co_u32_e32 v4, vcc, 0xc000, v2
	s_add_i32 s28, s28, s96
	s_nop 0
	v_addc_co_u32_e32 v5, vcc, 0, v3, vcc
	global_store_dword v[4:5], v10, off
	v_add_co_u32_e32 v4, vcc, 0x12000, v2
	s_cmpk_gt_i32 s28, 0x2ff
	s_nop 0
	v_addc_co_u32_e32 v5, vcc, 0, v3, vcc
	global_store_dword v[4:5], v11, off
	v_add_co_u32_e32 v4, vcc, 0x18000, v2
	s_nop 1
	v_addc_co_u32_e32 v5, vcc, 0, v3, vcc
	global_store_dword v[4:5], v8, off
	v_add_co_u32_e32 v4, vcc, 0x1e000, v2
	s_nop 1
	v_addc_co_u32_e32 v5, vcc, 0, v3, vcc
	global_store_dword v[4:5], v9, off
	v_add_co_u32_e32 v4, vcc, 0x24000, v2
	s_nop 1
	v_addc_co_u32_e32 v5, vcc, 0, v3, vcc
	v_add_co_u32_e32 v2, vcc, 0x2a000, v2
	global_store_dword v[4:5], v6, off
	s_nop 0
	v_addc_co_u32_e32 v3, vcc, 0, v3, vcc
	global_store_dword v[2:3], v7, off
	s_cbranch_scc0 .LBB0_10
; __device__ __forceinline__ void prologue(const Args& a, LAS unsigned char* lds) {
;     ...
;         for (int idx = blockIdx.x * 512 + tid; idx < T * 8; idx += gridDim.x * 512) {
;             const int row = idx >> 3, j = idx & 7;
;             const double rev = (double)a.pos[row] * c_inv_freq[j] * 0.15915494309189535;
;             const float fr = (float)(rev - floor(rev));
;             cs[(size_t)row * 16 + j] = __builtin_amdgcn_cosf(fr);
;             cs[(size_t)row * 16 + 8 + j] = __builtin_amdgcn_sinf(fr);
;         }
.LBB0_13:
	s_lshl_b32 s4, s2, 9
	s_lshl_b32 s3, s96, 9
	s_add_u32 s0, s94, 0x900000
	s_addc_u32 s1, s95, 0
	v_writelane_b32 v246, s0, 4
	v_add_u32_e32 v1, s4, v74
	s_nop 0
	v_writelane_b32 v246, s1, 5
	s_mov_b32 s0, 0x80000
	v_cmp_gt_i32_e32 vcc, s0, v1
	s_barrier
	v_writelane_b32 v246, s4, 6
	s_and_saveexec_b64 s[0:1], vcc
	s_cbranch_execz .LBB0_16
	v_and_b32_e32 v4, 7, v74
	v_lshlrev_b32_e32 v2, 3, v4
	s_getpc_b64 s[4:5]
	s_add_u32 s4, s4, c_inv_freq@rel32@lo+4
	s_addc_u32 s5, s5, c_inv_freq@rel32@hi+12
	global_load_dwordx2 v[2:3], v2, s[4:5]
	v_readlane_b32 s4, v246, 4
	v_lshlrev_b32_e32 v4, 2, v4
	v_mov_b32_e32 v5, 0
	v_readlane_b32 s5, v246, 5
	s_mov_b32 s6, 0x6dc9c883
	s_mov_b32 s7, 0x3fc45f30
	v_lshl_add_u64 v[4:5], s[4:5], 0, v[4:5]
	s_mov_b64 s[4:5], 0
	s_mov_b32 s12, 0x7ffff
	s_cmpk_eq_i32 s96, 0x100
	s_cbranch_scc0 .LBB0_15
	v_mov_b32_e32 v212, v1
	v_ashrrev_i32_e32 v208, 3, v212
	v_add_u32_e32 v212, s3, v212
	v_mov_b32_e32 v214, v208
	v_ashrrev_i32_e32 v215, 31, v214
	v_lshl_add_u64 v[214:215], v[214:215], 2, s[40:41]
	global_load_dword v216, v[214:215], off
	v_ashrrev_i32_e32 v209, 3, v212
	v_add_u32_e32 v212, s3, v212
	v_mov_b32_e32 v214, v209
	v_ashrrev_i32_e32 v215, 31, v214
	v_lshl_add_u64 v[214:215], v[214:215], 2, s[40:41]
	global_load_dword v217, v[214:215], off
	v_ashrrev_i32_e32 v210, 3, v212
	v_add_u32_e32 v212, s3, v212
	v_mov_b32_e32 v214, v210
	v_ashrrev_i32_e32 v215, 31, v214
	v_lshl_add_u64 v[214:215], v[214:215], 2, s[40:41]
	global_load_dword v218, v[214:215], off
	v_ashrrev_i32_e32 v211, 3, v212
	v_add_u32_e32 v212, s3, v212
	v_mov_b32_e32 v214, v211
	v_ashrrev_i32_e32 v215, 31, v214
	v_lshl_add_u64 v[214:215], v[214:215], 2, s[40:41]
	global_load_dword v219, v[214:215], off
	v_mov_b32_e32 v6, v208
	v_ashrrev_i32_e32 v7, 31, v6
	v_lshlrev_b64 v[6:7], 6, v[6:7]
	v_lshl_add_u64 v[6:7], v[4:5], 0, v[6:7]
	s_waitcnt vmcnt(3)
	v_mov_b32_e32 v8, v216
	v_cvt_f64_i32_e32 v[8:9], v8
	v_mul_f64 v[8:9], v[2:3], v[8:9]
	v_mul_f64 v[10:11], v[8:9], s[6:7]
	v_floor_f64_e32 v[10:11], v[10:11]
	v_fma_f64 v[8:9], v[8:9], s[6:7], -v[10:11]
	v_cvt_f32_f64_e32 v8, v[8:9]
	v_cos_f32_e32 v9, v8
	v_sin_f32_e32 v8, v8
	global_store_dword v[6:7], v9, off
	global_store_dword v[6:7], v8, off offset:32
	v_mov_b32_e32 v6, v209
	v_ashrrev_i32_e32 v7, 31, v6
	v_lshlrev_b64 v[6:7], 6, v[6:7]
	v_lshl_add_u64 v[6:7], v[4:5], 0, v[6:7]
	s_waitcnt vmcnt(4)
	v_mov_b32_e32 v8, v217
	v_cvt_f64_i32_e32 v[8:9], v8
	v_mul_f64 v[8:9], v[2:3], v[8:9]
	v_mul_f64 v[10:11], v[8:9], s[6:7]
	v_floor_f64_e32 v[10:11], v[10:11]
	v_fma_f64 v[8:9], v[8:9], s[6:7], -v[10:11]
	v_cvt_f32_f64_e32 v8, v[8:9]
	v_cos_f32_e32 v9, v8
	v_sin_f32_e32 v8, v8
	global_store_dword v[6:7], v9, off
	global_store_dword v[6:7], v8, off offset:32
	v_mov_b32_e32 v6, v210
	v_ashrrev_i32_e32 v7, 31, v6
	v_lshlrev_b64 v[6:7], 6, v[6:7]
	v_lshl_add_u64 v[6:7], v[4:5], 0, v[6:7]
	s_waitcnt vmcnt(5)
	v_mov_b32_e32 v8, v218
	v_cvt_f64_i32_e32 v[8:9], v8
	v_mul_f64 v[8:9], v[2:3], v[8:9]
	v_mul_f64 v[10:11], v[8:9], s[6:7]
	v_floor_f64_e32 v[10:11], v[10:11]
	v_fma_f64 v[8:9], v[8:9], s[6:7], -v[10:11]
	v_cvt_f32_f64_e32 v8, v[8:9]
	v_cos_f32_e32 v9, v8
	v_sin_f32_e32 v8, v8
	global_store_dword v[6:7], v9, off
	global_store_dword v[6:7], v8, off offset:32
	v_mov_b32_e32 v6, v211
	v_ashrrev_i32_e32 v7, 31, v6
	v_lshlrev_b64 v[6:7], 6, v[6:7]
	v_lshl_add_u64 v[6:7], v[4:5], 0, v[6:7]
	s_waitcnt vmcnt(6)
	v_mov_b32_e32 v8, v219
	v_cvt_f64_i32_e32 v[8:9], v8
	v_mul_f64 v[8:9], v[2:3], v[8:9]
	v_mul_f64 v[10:11], v[8:9], s[6:7]
	v_floor_f64_e32 v[10:11], v[10:11]
	v_fma_f64 v[8:9], v[8:9], s[6:7], -v[10:11]
	v_cvt_f32_f64_e32 v8, v[8:9]
	v_cos_f32_e32 v9, v8
	v_sin_f32_e32 v8, v8
	global_store_dword v[6:7], v9, off
	global_store_dword v[6:7], v8, off offset:32
	s_branch .LBB0_16
